# FFN-up epilogue: 104 causal-conv groups rewritten from 4 DPP movs + fma chain to DPP-fused fmac (bit-identical), on top of EpiRes residual prefetch
# speedup vs baseline: 1.0027x; 1.0027x over previous
; #define PG8_LAS __attribute__((address_space(3)))
;     __device__ __forceinline__ void operator()(f32x4 (&acc)[2][2][4][2], const Unit& u, int ui, int wr, int wc, int fr_, int fq_) const {
;     ...
;             for (int m = 0; m < 4; ++m) { const float r = rtab[ui * 256 + ai * HALF + wr * 64 + m * 16 + fr];
; #pragma unroll
;                 for (int bj = 0; bj < 2; ++bj)
; #pragma unroll
;                     for (int n = 0; n < 2; ++n) acc[ai][bj][m][n] = acc[ai][bj][m][n] * r; }
;     ...
;                 for (int ai = 0; ai < 2; ++ai) { const int kb = 2 * ai + wr;
;                     f32x4 c62 = (f32x4){0.f, 0.f, 0.f, 0.f}, c63 = c62;
;                     if (kb > 0) { c62 = *(const PG8_LAS f32x4*)(exch + (((kb - 1) * 2 + 0) * 256 + bj * HALF + 32 * wc + 8 * fq + 4 * n)); c63 = *(const PG8_LAS f32x4*)(exch + (((kb - 1) * 2 + 1) * 256 + bj * HALF + 32 * wc + 8 * fq + 4 * n)); }
; #pragma unroll
;                     for (int m = 3; m >= 0; --m) { f32x4 cur = acc[ai][bj][m][n], res;
; #pragma unroll
;                         for (int j = 0; j < 4; ++j) { const float c = cur[j]; const float pv = (m > 0) ? acc[ai][bj][m > 0 ? m - 1 : 0][n][j] : (fr == 15 ? c63[j] : c62[j]); float t1, t2;
;                             asm volatile("s_nop 1\n\tv_mov_b32_dpp %0, %3 row_ror:1 row_mask:0xf bank_mask:0xf\n\tv_mov_b32_dpp %1, %3 row_ror:2 row_mask:0xf bank_mask:0xf\n\t"
;                                          "v_mov_b32_dpp %0, %2 row_shr:1 row_mask:0xf bank_mask:0xf\n\tv_mov_b32_dpp %1, %2 row_shr:2 row_mask:0xf bank_mask:0xf"
;                                          : "=&v"(t1), "=&v"(t2) : "v"(c), "v"(pv));
;                             res[j] = bb[j] + w0[j] * t2 + w1[j] * t1 + w2[j] * c; }
;                         asm volatile("" : "+v"(res[0]), "+v"(res[1]), "+v"(res[2]), "+v"(res[3]));
;                         acc[ai][bj][m][n] = res; } }
.LBB0_1186:
	v_pk_mul_f32 v[102:103], v[102:103], v[196:197] op_sel_hi:[1,0]
	v_pk_mul_f32 v[104:105], v[104:105], v[196:197] op_sel_hi:[1,0]
	v_pk_mul_f32 v[106:107], v[106:107], v[194:195] op_sel_hi:[1,0]
	s_waitcnt vmcnt(0)
	v_mov_b32_e32 v211, v30
	v_fmac_f32_dpp v211, v152, v134 row_shr:2 row_mask:0xf bank_mask:0xf
	v_fmac_f32_dpp v211, v102, v134 row_shl:14 row_mask:0xf bank_mask:0xf
	v_fmac_f32_dpp v211, v152, v118 row_shr:1 row_mask:0xf bank_mask:0xf
	v_fmac_f32_dpp v211, v102, v118 row_shl:15 row_mask:0xf bank_mask:0xf
	v_fmac_f32_e32 v211, v152, v130
	v_pk_mul_f32 v[108:109], v[108:109], v[194:195] op_sel_hi:[1,0]
	v_mov_b32_e32 v212, v31
	v_fmac_f32_dpp v212, v153, v135 row_shr:2 row_mask:0xf bank_mask:0xf
	v_fmac_f32_dpp v212, v103, v135 row_shl:14 row_mask:0xf bank_mask:0xf
	v_fmac_f32_dpp v212, v153, v119 row_shr:1 row_mask:0xf bank_mask:0xf
	v_fmac_f32_dpp v212, v103, v119 row_shl:15 row_mask:0xf bank_mask:0xf
	v_fmac_f32_e32 v212, v153, v131
	v_cmp_eq_u32_e64 s[8:9], 15, v210
	v_mov_b32_e32 v152, v32
	v_fmac_f32_dpp v152, v154, v136 row_shr:2 row_mask:0xf bank_mask:0xf
	v_fmac_f32_dpp v152, v104, v136 row_shl:14 row_mask:0xf bank_mask:0xf
	v_fmac_f32_dpp v152, v154, v120 row_shr:1 row_mask:0xf bank_mask:0xf
	v_fmac_f32_dpp v152, v104, v120 row_shl:15 row_mask:0xf bank_mask:0xf
	v_fmac_f32_e32 v152, v154, v132
	s_andn2_b64 vcc, exec, s[40:41]
	v_mov_b32_e32 v153, v33
	v_fmac_f32_dpp v153, v155, v137 row_shr:2 row_mask:0xf bank_mask:0xf
	v_fmac_f32_dpp v153, v105, v137 row_shl:14 row_mask:0xf bank_mask:0xf
	v_fmac_f32_dpp v153, v155, v121 row_shr:1 row_mask:0xf bank_mask:0xf
	v_fmac_f32_dpp v153, v105, v121 row_shl:15 row_mask:0xf bank_mask:0xf
	v_fmac_f32_e32 v153, v155, v133
	v_lshl_add_u32 v227, v143, 2, s86
	v_mov_b32_e32 v213, v30
	v_fmac_f32_dpp v213, v102, v134 row_shr:2 row_mask:0xf bank_mask:0xf
	v_fmac_f32_dpp v213, v106, v134 row_shl:14 row_mask:0xf bank_mask:0xf
	v_fmac_f32_dpp v213, v102, v118 row_shr:1 row_mask:0xf bank_mask:0xf
	v_fmac_f32_dpp v213, v106, v118 row_shl:15 row_mask:0xf bank_mask:0xf
	v_fmac_f32_e32 v213, v102, v130
	v_mov_b32_e32 v143, 0
	v_mov_b32_e32 v216, v31
	v_fmac_f32_dpp v216, v103, v135 row_shr:2 row_mask:0xf bank_mask:0xf
	v_fmac_f32_dpp v216, v107, v135 row_shl:14 row_mask:0xf bank_mask:0xf
	v_fmac_f32_dpp v216, v103, v119 row_shr:1 row_mask:0xf bank_mask:0xf
	v_fmac_f32_dpp v216, v107, v119 row_shl:15 row_mask:0xf bank_mask:0xf
	v_fmac_f32_e32 v216, v103, v131
	s_nop 0
	v_mov_b32_e32 v154, v32
	v_fmac_f32_dpp v154, v104, v136 row_shr:2 row_mask:0xf bank_mask:0xf
	v_fmac_f32_dpp v154, v108, v136 row_shl:14 row_mask:0xf bank_mask:0xf
	v_fmac_f32_dpp v154, v104, v120 row_shr:1 row_mask:0xf bank_mask:0xf
	v_fmac_f32_dpp v154, v108, v120 row_shl:15 row_mask:0xf bank_mask:0xf
	v_fmac_f32_e32 v154, v104, v132
	v_mov_b32_e32 v214, v33
	v_fmac_f32_dpp v214, v105, v137 row_shr:2 row_mask:0xf bank_mask:0xf
	v_fmac_f32_dpp v214, v109, v137 row_shl:14 row_mask:0xf bank_mask:0xf
	v_fmac_f32_dpp v214, v105, v121 row_shr:1 row_mask:0xf bank_mask:0xf
	v_fmac_f32_dpp v214, v109, v121 row_shl:15 row_mask:0xf bank_mask:0xf
	v_fmac_f32_e32 v214, v105, v133
	s_waitcnt lgkmcnt(0)
	v_cndmask_b32_e64 v105, v144, v148, s[8:9]
	v_mov_b32_e32 v218, v30
	v_fmac_f32_dpp v218, v106, v134 row_shr:2 row_mask:0xf bank_mask:0xf
	v_fmac_f32_dpp v218, v138, v134 row_shl:14 row_mask:0xf bank_mask:0xf
	v_fmac_f32_dpp v218, v106, v118 row_shr:1 row_mask:0xf bank_mask:0xf
	v_fmac_f32_dpp v218, v138, v118 row_shl:15 row_mask:0xf bank_mask:0xf
	v_fmac_f32_e32 v218, v106, v130
	v_mov_b32_e32 v220, v31
	v_fmac_f32_dpp v220, v107, v135 row_shr:2 row_mask:0xf bank_mask:0xf
	v_fmac_f32_dpp v220, v139, v135 row_shl:14 row_mask:0xf bank_mask:0xf
	v_fmac_f32_dpp v220, v107, v119 row_shr:1 row_mask:0xf bank_mask:0xf
	v_fmac_f32_dpp v220, v139, v119 row_shl:15 row_mask:0xf bank_mask:0xf
	v_fmac_f32_e32 v220, v107, v131
	v_mov_b32_e32 v217, v32
	v_fmac_f32_dpp v217, v108, v136 row_shr:2 row_mask:0xf bank_mask:0xf
	v_fmac_f32_dpp v217, v140, v136 row_shl:14 row_mask:0xf bank_mask:0xf
	v_fmac_f32_dpp v217, v108, v120 row_shr:1 row_mask:0xf bank_mask:0xf
	v_fmac_f32_dpp v217, v140, v120 row_shl:15 row_mask:0xf bank_mask:0xf
	v_fmac_f32_e32 v217, v108, v132
	v_mov_b32_e32 v219, v33
	v_fmac_f32_dpp v219, v109, v137 row_shr:2 row_mask:0xf bank_mask:0xf
	v_fmac_f32_dpp v219, v141, v137 row_shl:14 row_mask:0xf bank_mask:0xf
	v_fmac_f32_dpp v219, v109, v121 row_shr:1 row_mask:0xf bank_mask:0xf
	v_fmac_f32_dpp v219, v141, v121 row_shl:15 row_mask:0xf bank_mask:0xf
	v_fmac_f32_e32 v219, v109, v133
	v_cndmask_b32_e64 v104, v145, v149, s[8:9]
	v_mov_b32_e32 v223, v30
	v_fmac_f32_dpp v223, v138, v134 row_shr:2 row_mask:0xf bank_mask:0xf
	v_fmac_f32_dpp v223, v105, v134 row_shl:14 row_mask:0xf bank_mask:0xf
	v_fmac_f32_dpp v223, v138, v118 row_shr:1 row_mask:0xf bank_mask:0xf
	v_fmac_f32_dpp v223, v105, v118 row_shl:15 row_mask:0xf bank_mask:0xf
	v_cndmask_b32_e64 v103, v146, v150, s[8:9]
	v_mov_b32_e32 v224, v31
	v_fmac_f32_dpp v224, v139, v135 row_shr:2 row_mask:0xf bank_mask:0xf
	v_fmac_f32_dpp v224, v104, v135 row_shl:14 row_mask:0xf bank_mask:0xf
	v_fmac_f32_dpp v224, v139, v119 row_shr:1 row_mask:0xf bank_mask:0xf
	v_fmac_f32_dpp v224, v104, v119 row_shl:15 row_mask:0xf bank_mask:0xf
	v_cndmask_b32_e64 v102, v147, v151, s[8:9]
	v_mov_b32_e32 v221, v32
	v_fmac_f32_dpp v221, v140, v136 row_shr:2 row_mask:0xf bank_mask:0xf
	v_fmac_f32_dpp v221, v103, v136 row_shl:14 row_mask:0xf bank_mask:0xf
	v_fmac_f32_dpp v221, v140, v120 row_shr:1 row_mask:0xf bank_mask:0xf
	v_fmac_f32_dpp v221, v103, v120 row_shl:15 row_mask:0xf bank_mask:0xf
	s_nop 1
	v_mov_b32_dpp v103, v102 row_ror:1 row_mask:0xf bank_mask:0xf
	v_mov_b32_dpp v104, v102 row_ror:2 row_mask:0xf bank_mask:0xf
	v_mov_b32_dpp v103, v141 row_shr:1 row_mask:0xf bank_mask:0xf
	v_mov_b32_dpp v104, v141 row_shr:2 row_mask:0xf bank_mask:0xf
	v_cndmask_b32_e64 v102, 0, 1, s[40:41]
	v_fma_f32 v222, v137, v104, v33
	v_fmac_f32_e32 v222, v121, v103
	v_fmac_f32_e32 v223, v138, v130
	v_fmac_f32_e32 v224, v139, v131
	v_fmac_f32_e32 v221, v140, v132
	v_fmac_f32_e32 v222, v141, v133
	v_cmp_ne_u32_e64 s[12:13], 1, v102
	v_mov_b32_e32 v144, 0
	v_mov_b32_e32 v145, 0
	v_mov_b32_e32 v102, 0
	v_mov_b32_e32 v103, 0
	v_mov_b32_e32 v104, 0
	v_mov_b32_e32 v105, 0
	s_cbranch_vccnz .LBB0_1188
	ds_read_b128 v[142:145], v227 offset:2048
	ds_read_b128 v[102:105], v227 offset:3072
; #define PG8_LAS __attribute__((address_space(3)))
;     __device__ __forceinline__ void operator()(f32x4 (&acc)[2][2][4][2], const Unit& u, int ui, int wr, int wc, int fr_, int fq_) const {
;     ...
;             for (int m = 0; m < 4; ++m) { const float r = rtab[ui * 256 + ai * HALF + wr * 64 + m * 16 + fr];
; #pragma unroll
;                 for (int bj = 0; bj < 2; ++bj)
; #pragma unroll
;                     for (int n = 0; n < 2; ++n) acc[ai][bj][m][n] = acc[ai][bj][m][n] * r; }
;     ...
;             for (int n = 0; n < 2; ++n) { const int ch = bj * 2816 + fbase + 4 * n;
;                 const f32x4 w0 = *(const f32x4*)(cw + ch), w1 = *(const f32x4*)(cw + 5632 + ch), w2 = *(const f32x4*)(cw + 2 * 5632 + ch), bb = *(const f32x4*)(cb + ch);
; #pragma unroll
;                 for (int ai = 0; ai < 2; ++ai) { const int kb = 2 * ai + wr;
;                     f32x4 c62 = (f32x4){0.f, 0.f, 0.f, 0.f}, c63 = c62;
;                     if (kb > 0) { c62 = *(const PG8_LAS f32x4*)(exch + (((kb - 1) * 2 + 0) * 256 + bj * HALF + 32 * wc + 8 * fq + 4 * n)); c63 = *(const PG8_LAS f32x4*)(exch + (((kb - 1) * 2 + 1) * 256 + bj * HALF + 32 * wc + 8 * fq + 4 * n)); }
; #pragma unroll
;                     for (int m = 3; m >= 0; --m) { f32x4 cur = acc[ai][bj][m][n], res;
; #pragma unroll
;                         for (int j = 0; j < 4; ++j) { const float c = cur[j]; const float pv = (m > 0) ? acc[ai][bj][m > 0 ? m - 1 : 0][n][j] : (fr == 15 ? c63[j] : c62[j]); float t1, t2;
;                             asm volatile("s_nop 1\n\tv_mov_b32_dpp %0, %3 row_ror:1 row_mask:0xf bank_mask:0xf\n\tv_mov_b32_dpp %1, %3 row_ror:2 row_mask:0xf bank_mask:0xf\n\t"
;                                          "v_mov_b32_dpp %0, %2 row_shr:1 row_mask:0xf bank_mask:0xf\n\tv_mov_b32_dpp %1, %2 row_shr:2 row_mask:0xf bank_mask:0xf"
;                                          : "=&v"(t1), "=&v"(t2) : "v"(c), "v"(pv));
;                             res[j] = bb[j] + w0[j] * t2 + w1[j] * t1 + w2[j] * c; }
;                         asm volatile("" : "+v"(res[0]), "+v"(res[1]), "+v"(res[2]), "+v"(res[3]));
;                         acc[ai][bj][m][n] = res; } }
.LBB0_1188:
	v_pk_mul_f32 v[46:47], v[46:47], v[188:189] op_sel_hi:[1,0]
	v_pk_mul_f32 v[48:49], v[48:49], v[188:189] op_sel_hi:[1,0]
	v_pk_mul_f32 v[90:91], v[90:91], v[190:191] op_sel_hi:[1,0]
	v_mov_b32_e32 v139, v30
	v_fmac_f32_dpp v139, v126, v134 row_shr:2 row_mask:0xf bank_mask:0xf
	v_fmac_f32_dpp v139, v46, v134 row_shl:14 row_mask:0xf bank_mask:0xf
	v_fmac_f32_dpp v139, v126, v118 row_shr:1 row_mask:0xf bank_mask:0xf
	v_fmac_f32_dpp v139, v46, v118 row_shl:15 row_mask:0xf bank_mask:0xf
	v_fmac_f32_e32 v139, v126, v130
	v_mov_b32_e32 v141, v31
	v_fmac_f32_dpp v141, v127, v135 row_shr:2 row_mask:0xf bank_mask:0xf
	v_fmac_f32_dpp v141, v47, v135 row_shl:14 row_mask:0xf bank_mask:0xf
	v_fmac_f32_dpp v141, v127, v119 row_shr:1 row_mask:0xf bank_mask:0xf
	v_fmac_f32_dpp v141, v47, v119 row_shl:15 row_mask:0xf bank_mask:0xf
	v_fmac_f32_e32 v141, v127, v131
	v_mov_b32_e32 v138, v32
	v_fmac_f32_dpp v138, v128, v136 row_shr:2 row_mask:0xf bank_mask:0xf
	v_fmac_f32_dpp v138, v48, v136 row_shl:14 row_mask:0xf bank_mask:0xf
	v_fmac_f32_dpp v138, v128, v120 row_shr:1 row_mask:0xf bank_mask:0xf
	v_fmac_f32_dpp v138, v48, v120 row_shl:15 row_mask:0xf bank_mask:0xf
	v_fmac_f32_e32 v138, v128, v132
	v_mov_b32_e32 v140, v33
	v_fmac_f32_dpp v140, v129, v137 row_shr:2 row_mask:0xf bank_mask:0xf
	v_fmac_f32_dpp v140, v49, v137 row_shl:14 row_mask:0xf bank_mask:0xf
	v_fmac_f32_dpp v140, v129, v121 row_shr:1 row_mask:0xf bank_mask:0xf
	v_fmac_f32_dpp v140, v49, v121 row_shl:15 row_mask:0xf bank_mask:0xf
	v_fmac_f32_e32 v140, v129, v133
	v_pk_mul_f32 v[92:93], v[92:93], v[190:191] op_sel_hi:[1,0]
	v_mov_b32_e32 v147, v30
	v_fmac_f32_dpp v147, v46, v134 row_shr:2 row_mask:0xf bank_mask:0xf
	v_fmac_f32_dpp v147, v90, v134 row_shl:14 row_mask:0xf bank_mask:0xf
	v_fmac_f32_dpp v147, v46, v118 row_shr:1 row_mask:0xf bank_mask:0xf
	v_fmac_f32_dpp v147, v90, v118 row_shl:15 row_mask:0xf bank_mask:0xf
	v_fmac_f32_e32 v147, v46, v130
	v_pk_mul_f32 v[94:95], v[94:95], v[192:193] op_sel_hi:[1,0]
	v_mov_b32_e32 v149, v31
	v_fmac_f32_dpp v149, v47, v135 row_shr:2 row_mask:0xf bank_mask:0xf
	v_fmac_f32_dpp v149, v91, v135 row_shl:14 row_mask:0xf bank_mask:0xf
	v_fmac_f32_dpp v149, v47, v119 row_shr:1 row_mask:0xf bank_mask:0xf
	v_fmac_f32_dpp v149, v91, v119 row_shl:15 row_mask:0xf bank_mask:0xf
	v_fmac_f32_e32 v149, v47, v131
	v_pk_mul_f32 v[96:97], v[96:97], v[192:193] op_sel_hi:[1,0]
	v_mov_b32_e32 v146, v32
	v_fmac_f32_dpp v146, v48, v136 row_shr:2 row_mask:0xf bank_mask:0xf
	v_fmac_f32_dpp v146, v92, v136 row_shl:14 row_mask:0xf bank_mask:0xf
	v_fmac_f32_dpp v146, v48, v120 row_shr:1 row_mask:0xf bank_mask:0xf
	v_fmac_f32_dpp v146, v92, v120 row_shl:15 row_mask:0xf bank_mask:0xf
	v_fmac_f32_e32 v146, v48, v132
	v_mov_b32_e32 v148, v33
	v_fmac_f32_dpp v148, v49, v137 row_shr:2 row_mask:0xf bank_mask:0xf
	v_fmac_f32_dpp v148, v93, v137 row_shl:14 row_mask:0xf bank_mask:0xf
	v_fmac_f32_dpp v148, v49, v121 row_shr:1 row_mask:0xf bank_mask:0xf
	v_fmac_f32_dpp v148, v93, v121 row_shl:15 row_mask:0xf bank_mask:0xf
	v_fmac_f32_e32 v148, v49, v133
	s_waitcnt lgkmcnt(0)
	v_cndmask_b32_e64 v49, v142, v102, s[8:9]
	v_mov_b32_e32 v151, v30
	v_fmac_f32_dpp v151, v90, v134 row_shr:2 row_mask:0xf bank_mask:0xf
	v_fmac_f32_dpp v151, v94, v134 row_shl:14 row_mask:0xf bank_mask:0xf
	v_fmac_f32_dpp v151, v90, v118 row_shr:1 row_mask:0xf bank_mask:0xf
	v_fmac_f32_dpp v151, v94, v118 row_shl:15 row_mask:0xf bank_mask:0xf
	v_fmac_f32_e32 v151, v90, v130
	v_mov_b32_e32 v215, v31
	v_fmac_f32_dpp v215, v91, v135 row_shr:2 row_mask:0xf bank_mask:0xf
	v_fmac_f32_dpp v215, v95, v135 row_shl:14 row_mask:0xf bank_mask:0xf
	v_fmac_f32_dpp v215, v91, v119 row_shr:1 row_mask:0xf bank_mask:0xf
	v_fmac_f32_dpp v215, v95, v119 row_shl:15 row_mask:0xf bank_mask:0xf
	v_fmac_f32_e32 v215, v91, v131
	v_mov_b32_e32 v150, v32
	v_fmac_f32_dpp v150, v92, v136 row_shr:2 row_mask:0xf bank_mask:0xf
	v_fmac_f32_dpp v150, v96, v136 row_shl:14 row_mask:0xf bank_mask:0xf
	v_fmac_f32_dpp v150, v92, v120 row_shr:1 row_mask:0xf bank_mask:0xf
	v_fmac_f32_dpp v150, v96, v120 row_shl:15 row_mask:0xf bank_mask:0xf
	v_fmac_f32_e32 v150, v92, v132
	v_mov_b32_e32 v155, v33
	v_fmac_f32_dpp v155, v93, v137 row_shr:2 row_mask:0xf bank_mask:0xf
	v_fmac_f32_dpp v155, v97, v137 row_shl:14 row_mask:0xf bank_mask:0xf
	v_fmac_f32_dpp v155, v93, v121 row_shr:1 row_mask:0xf bank_mask:0xf
	v_fmac_f32_dpp v155, v97, v121 row_shl:15 row_mask:0xf bank_mask:0xf
	v_fmac_f32_e32 v155, v93, v133
	s_nop 1
	v_mov_b32_dpp v90, v49 row_ror:1 row_mask:0xf bank_mask:0xf
	v_mov_b32_dpp v91, v49 row_ror:2 row_mask:0xf bank_mask:0xf
	v_mov_b32_dpp v90, v94 row_shr:1 row_mask:0xf bank_mask:0xf
	v_mov_b32_dpp v91, v94 row_shr:2 row_mask:0xf bank_mask:0xf
	v_cndmask_b32_e64 v48, v143, v103, s[8:9]
	v_fma_f32 v134, v134, v91, v30
	v_fmac_f32_e32 v134, v118, v90
	v_fmac_f32_e32 v134, v94, v130
	v_cndmask_b32_e64 v47, v144, v104, s[8:9]
	v_mov_b32_e32 v130, v31
	v_fmac_f32_dpp v130, v95, v135 row_shr:2 row_mask:0xf bank_mask:0xf
	v_fmac_f32_dpp v130, v48, v135 row_shl:14 row_mask:0xf bank_mask:0xf
	v_fmac_f32_dpp v130, v95, v119 row_shr:1 row_mask:0xf bank_mask:0xf
	v_fmac_f32_dpp v130, v48, v119 row_shl:15 row_mask:0xf bank_mask:0xf
	s_nop 1
	v_mov_b32_dpp v30, v47 row_ror:1 row_mask:0xf bank_mask:0xf
	v_mov_b32_dpp v31, v47 row_ror:2 row_mask:0xf bank_mask:0xf
	v_mov_b32_dpp v30, v96 row_shr:1 row_mask:0xf bank_mask:0xf
	v_mov_b32_dpp v31, v96 row_shr:2 row_mask:0xf bank_mask:0xf
	v_cndmask_b32_e64 v46, v145, v105, s[8:9]
	v_fma_f32 v32, v136, v31, v32
	v_fmac_f32_e32 v32, v120, v30
	s_nop 1
	v_mov_b32_dpp v30, v46 row_ror:1 row_mask:0xf bank_mask:0xf
	v_mov_b32_dpp v31, v46 row_ror:2 row_mask:0xf bank_mask:0xf
	v_mov_b32_dpp v30, v97 row_shr:1 row_mask:0xf bank_mask:0xf
	v_mov_b32_dpp v31, v97 row_shr:2 row_mask:0xf bank_mask:0xf
	v_fmac_f32_e32 v130, v95, v131
	v_fmac_f32_e32 v33, v137, v31
	v_fmac_f32_e32 v33, v121, v30
	v_or_b32_e32 v30, 4, v186
	v_ashrrev_i32_e32 v31, 31, v30
	v_fmac_f32_e32 v32, v96, v132
	v_fmac_f32_e32 v33, v97, v133
	v_lshlrev_b64 v[30:31], 2, v[30:31]
	v_lshl_add_u64 v[46:47], s[20:21], 0, v[30:31]
	global_load_dwordx4 v[90:93], v[204:205], off offset:16
	v_lshl_add_u64 v[30:31], s[22:23], 0, v[30:31]
	global_load_dwordx4 v[102:105], v[46:47], off
	global_load_dwordx4 v[94:97], v[30:31], off
	s_nop 0
	global_load_dwordx4 v[46:49], v[198:199], off offset:16
	v_mov_b32_e32 v106, 0
	s_and_b64 vcc, exec, s[10:11]
	v_mov_b32_e32 v118, 0
	v_mov_b32_e32 v119, 0
	v_mov_b32_e32 v120, 0
	v_mov_b32_e32 v121, 0
	v_mov_b32_e32 v126, 0
	v_mov_b32_e32 v127, 0
	v_mov_b32_e32 v128, 0
	v_mov_b32_e32 v129, 0
	s_cbranch_vccnz .LBB0_1190
	v_add_u32_e32 v31, 0xfffff810, v227
	v_add_u32_e32 v30, 0xfffffc10, v227
	ds_read_b128 v[118:121], v31
	ds_read_b128 v[126:129], v30
; #define PG8_LAS __attribute__((address_space(3)))
;     __device__ __forceinline__ void operator()(f32x4 (&acc)[2][2][4][2], const Unit& u, int ui, int wr, int wc, int fr_, int fq_) const {
;     ...
;             for (int m = 0; m < 4; ++m) { const float r = rtab[ui * 256 + ai * HALF + wr * 64 + m * 16 + fr];
; #pragma unroll
;                 for (int bj = 0; bj < 2; ++bj)
; #pragma unroll
;                     for (int n = 0; n < 2; ++n) acc[ai][bj][m][n] = acc[ai][bj][m][n] * r; }
;     ...
;             for (int n = 0; n < 2; ++n) { const int ch = bj * 2816 + fbase + 4 * n;
;                 const f32x4 w0 = *(const f32x4*)(cw + ch), w1 = *(const f32x4*)(cw + 5632 + ch), w2 = *(const f32x4*)(cw + 2 * 5632 + ch), bb = *(const f32x4*)(cb + ch);
; #pragma unroll
;                 for (int ai = 0; ai < 2; ++ai) { const int kb = 2 * ai + wr;
;                     f32x4 c62 = (f32x4){0.f, 0.f, 0.f, 0.f}, c63 = c62;
;                     if (kb > 0) { c62 = *(const PG8_LAS f32x4*)(exch + (((kb - 1) * 2 + 0) * 256 + bj * HALF + 32 * wc + 8 * fq + 4 * n)); c63 = *(const PG8_LAS f32x4*)(exch + (((kb - 1) * 2 + 1) * 256 + bj * HALF + 32 * wc + 8 * fq + 4 * n)); }
; #pragma unroll
;                     for (int m = 3; m >= 0; --m) { f32x4 cur = acc[ai][bj][m][n], res;
; #pragma unroll
;                         for (int j = 0; j < 4; ++j) { const float c = cur[j]; const float pv = (m > 0) ? acc[ai][bj][m > 0 ? m - 1 : 0][n][j] : (fr == 15 ? c63[j] : c62[j]); float t1, t2;
;                             asm volatile("s_nop 1\n\tv_mov_b32_dpp %0, %3 row_ror:1 row_mask:0xf bank_mask:0xf\n\tv_mov_b32_dpp %1, %3 row_ror:2 row_mask:0xf bank_mask:0xf\n\t"
;                                          "v_mov_b32_dpp %0, %2 row_shr:1 row_mask:0xf bank_mask:0xf\n\tv_mov_b32_dpp %1, %2 row_shr:2 row_mask:0xf bank_mask:0xf"
;                                          : "=&v"(t1), "=&v"(t2) : "v"(c), "v"(pv));
;                             res[j] = bb[j] + w0[j] * t2 + w1[j] * t1 + w2[j] * c; }
;                         asm volatile("" : "+v"(res[0]), "+v"(res[1]), "+v"(res[2]), "+v"(res[3]));
;                         acc[ai][bj][m][n] = res; } }
.LBB0_1190:
	v_mov_b32_e32 v30, v194
	v_mov_b32_e32 v31, v194
	v_mov_b32_e32 v197, v196
	v_pk_mul_f32 v[30:31], v[80:81], v[30:31]
	v_mov_b32_e32 v80, v196
	v_mov_b32_e32 v81, v196
	v_pk_mul_f32 v[76:77], v[76:77], v[80:81]
	v_pk_mul_f32 v[74:75], v[74:75], v[196:197]
	v_mov_b32_e32 v195, v194
	v_pk_mul_f32 v[78:79], v[78:79], v[194:195]
	s_waitcnt vmcnt(0)
	v_mov_b32_e32 v133, v46
	v_fmac_f32_dpp v133, v110, v90 row_shr:2 row_mask:0xf bank_mask:0xf
	v_fmac_f32_dpp v133, v74, v90 row_shl:14 row_mask:0xf bank_mask:0xf
	v_fmac_f32_dpp v133, v110, v102 row_shr:1 row_mask:0xf bank_mask:0xf
	v_fmac_f32_dpp v133, v74, v102 row_shl:15 row_mask:0xf bank_mask:0xf
	v_fmac_f32_e32 v133, v110, v94
	v_mov_b32_e32 v131, v47
	v_fmac_f32_dpp v131, v111, v91 row_shr:2 row_mask:0xf bank_mask:0xf
	v_fmac_f32_dpp v131, v75, v91 row_shl:14 row_mask:0xf bank_mask:0xf
	v_fmac_f32_dpp v131, v111, v103 row_shr:1 row_mask:0xf bank_mask:0xf
	v_fmac_f32_dpp v131, v75, v103 row_shl:15 row_mask:0xf bank_mask:0xf
	v_fmac_f32_e32 v131, v111, v95
	v_mov_b32_e32 v132, v48
	v_fmac_f32_dpp v132, v112, v92 row_shr:2 row_mask:0xf bank_mask:0xf
	v_fmac_f32_dpp v132, v76, v92 row_shl:14 row_mask:0xf bank_mask:0xf
	v_fmac_f32_dpp v132, v112, v104 row_shr:1 row_mask:0xf bank_mask:0xf
	v_fmac_f32_dpp v132, v76, v104 row_shl:15 row_mask:0xf bank_mask:0xf
	v_fmac_f32_e32 v132, v112, v96
	v_mov_b32_e32 v135, v49
	v_fmac_f32_dpp v135, v113, v93 row_shr:2 row_mask:0xf bank_mask:0xf
	v_fmac_f32_dpp v135, v77, v93 row_shl:14 row_mask:0xf bank_mask:0xf
	v_fmac_f32_dpp v135, v113, v105 row_shr:1 row_mask:0xf bank_mask:0xf
	v_fmac_f32_dpp v135, v77, v105 row_shl:15 row_mask:0xf bank_mask:0xf
	v_fmac_f32_e32 v135, v113, v97
	s_and_b64 vcc, exec, s[12:13]
	v_mov_b32_e32 v142, v46
	v_fmac_f32_dpp v142, v74, v90 row_shr:2 row_mask:0xf bank_mask:0xf
	v_fmac_f32_dpp v142, v78, v90 row_shl:14 row_mask:0xf bank_mask:0xf
	v_fmac_f32_dpp v142, v74, v102 row_shr:1 row_mask:0xf bank_mask:0xf
	v_fmac_f32_dpp v142, v78, v102 row_shl:15 row_mask:0xf bank_mask:0xf
	v_fmac_f32_e32 v142, v74, v94
	v_mov_b32_e32 v107, 0
	v_mov_b32_e32 v136, v47
	v_fmac_f32_dpp v136, v75, v91 row_shr:2 row_mask:0xf bank_mask:0xf
	v_fmac_f32_dpp v136, v79, v91 row_shl:14 row_mask:0xf bank_mask:0xf
	v_fmac_f32_dpp v136, v75, v103 row_shr:1 row_mask:0xf bank_mask:0xf
	v_fmac_f32_dpp v136, v79, v103 row_shl:15 row_mask:0xf bank_mask:0xf
	v_fmac_f32_e32 v136, v75, v95
	v_mov_b32_e32 v108, 0
	v_mov_b32_e32 v137, v48
	v_fmac_f32_dpp v137, v76, v92 row_shr:2 row_mask:0xf bank_mask:0xf
	v_fmac_f32_dpp v137, v30, v92 row_shl:14 row_mask:0xf bank_mask:0xf
	v_fmac_f32_dpp v137, v76, v104 row_shr:1 row_mask:0xf bank_mask:0xf
	v_fmac_f32_dpp v137, v30, v104 row_shl:15 row_mask:0xf bank_mask:0xf
	v_fmac_f32_e32 v137, v76, v96
	v_mov_b32_e32 v143, v49
	v_fmac_f32_dpp v143, v77, v93 row_shr:2 row_mask:0xf bank_mask:0xf
	v_fmac_f32_dpp v143, v31, v93 row_shl:14 row_mask:0xf bank_mask:0xf
	v_fmac_f32_dpp v143, v77, v105 row_shr:1 row_mask:0xf bank_mask:0xf
	v_fmac_f32_dpp v143, v31, v105 row_shl:15 row_mask:0xf bank_mask:0xf
	v_fmac_f32_e32 v143, v77, v97
	v_mov_b32_e32 v109, 0
	v_mov_b32_e32 v225, v46
	v_fmac_f32_dpp v225, v78, v90 row_shr:2 row_mask:0xf bank_mask:0xf
	v_fmac_f32_dpp v225, v122, v90 row_shl:14 row_mask:0xf bank_mask:0xf
	v_fmac_f32_dpp v225, v78, v102 row_shr:1 row_mask:0xf bank_mask:0xf
	v_fmac_f32_dpp v225, v122, v102 row_shl:15 row_mask:0xf bank_mask:0xf
	v_fmac_f32_e32 v225, v78, v94
	v_mov_b32_e32 v144, v47
	v_fmac_f32_dpp v144, v79, v91 row_shr:2 row_mask:0xf bank_mask:0xf
	v_fmac_f32_dpp v144, v123, v91 row_shl:14 row_mask:0xf bank_mask:0xf
	v_fmac_f32_dpp v144, v79, v103 row_shr:1 row_mask:0xf bank_mask:0xf
	v_fmac_f32_dpp v144, v123, v103 row_shl:15 row_mask:0xf bank_mask:0xf
	v_fmac_f32_e32 v144, v79, v95
	v_mov_b32_e32 v145, v48
	v_fmac_f32_dpp v145, v30, v92 row_shr:2 row_mask:0xf bank_mask:0xf
	v_fmac_f32_dpp v145, v124, v92 row_shl:14 row_mask:0xf bank_mask:0xf
	v_fmac_f32_dpp v145, v30, v104 row_shr:1 row_mask:0xf bank_mask:0xf
	v_fmac_f32_dpp v145, v124, v104 row_shl:15 row_mask:0xf bank_mask:0xf
	v_fmac_f32_e32 v145, v30, v96
	s_waitcnt lgkmcnt(0)
	v_cndmask_b32_e64 v75, v118, v126, s[8:9]
	v_mov_b32_e32 v226, v49
	v_fmac_f32_dpp v226, v31, v93 row_shr:2 row_mask:0xf bank_mask:0xf
	v_fmac_f32_dpp v226, v125, v93 row_shl:14 row_mask:0xf bank_mask:0xf
	v_fmac_f32_dpp v226, v31, v105 row_shr:1 row_mask:0xf bank_mask:0xf
	v_fmac_f32_dpp v226, v125, v105 row_shl:15 row_mask:0xf bank_mask:0xf
	v_fmac_f32_e32 v226, v31, v97
	v_cndmask_b32_e64 v74, v119, v127, s[8:9]
	v_mov_b32_e32 v126, v46
	v_fmac_f32_dpp v126, v122, v90 row_shr:2 row_mask:0xf bank_mask:0xf
	v_fmac_f32_dpp v126, v75, v90 row_shl:14 row_mask:0xf bank_mask:0xf
	v_fmac_f32_dpp v126, v122, v102 row_shr:1 row_mask:0xf bank_mask:0xf
	v_fmac_f32_dpp v126, v75, v102 row_shl:15 row_mask:0xf bank_mask:0xf
	v_fmac_f32_e32 v126, v122, v94
	v_cndmask_b32_e64 v31, v120, v128, s[8:9]
	v_mov_b32_e32 v122, v47
	v_fmac_f32_dpp v122, v123, v91 row_shr:2 row_mask:0xf bank_mask:0xf
	v_fmac_f32_dpp v122, v74, v91 row_shl:14 row_mask:0xf bank_mask:0xf
	v_fmac_f32_dpp v122, v123, v103 row_shr:1 row_mask:0xf bank_mask:0xf
	v_fmac_f32_dpp v122, v74, v103 row_shl:15 row_mask:0xf bank_mask:0xf
	v_fmac_f32_e32 v122, v123, v95
	v_cndmask_b32_e64 v30, v121, v129, s[8:9]
	v_mov_b32_e32 v123, v48
	v_fmac_f32_dpp v123, v124, v92 row_shr:2 row_mask:0xf bank_mask:0xf
	v_fmac_f32_dpp v123, v31, v92 row_shl:14 row_mask:0xf bank_mask:0xf
	v_fmac_f32_dpp v123, v124, v104 row_shr:1 row_mask:0xf bank_mask:0xf
	v_fmac_f32_dpp v123, v31, v104 row_shl:15 row_mask:0xf bank_mask:0xf
	v_fmac_f32_e32 v123, v124, v96
	v_mov_b32_e32 v75, 0
	v_mov_b32_e32 v124, v49
	v_fmac_f32_dpp v124, v125, v93 row_shr:2 row_mask:0xf bank_mask:0xf
	v_fmac_f32_dpp v124, v30, v93 row_shl:14 row_mask:0xf bank_mask:0xf
	v_fmac_f32_dpp v124, v125, v105 row_shr:1 row_mask:0xf bank_mask:0xf
	v_fmac_f32_dpp v124, v30, v105 row_shl:15 row_mask:0xf bank_mask:0xf
	v_fmac_f32_e32 v124, v125, v97
	v_mov_b32_e32 v74, 0
	v_mov_b32_e32 v76, 0
	v_mov_b32_e32 v77, 0
	s_cbranch_vccnz .LBB0_1192
	ds_read_b128 v[106:109], v227 offset:2064
	ds_read_b128 v[74:77], v227 offset:3088
; #define PG8_LAS __attribute__((address_space(3)))
;     __device__ __forceinline__ void operator()(f32x4 (&acc)[2][2][4][2], const Unit& u, int ui, int wr, int wc, int fr_, int fq_) const {
;     ...
;             for (int m = 0; m < 4; ++m) { const float r = rtab[ui * 256 + ai * HALF + wr * 64 + m * 16 + fr];
; #pragma unroll
;                 for (int bj = 0; bj < 2; ++bj)
; #pragma unroll
;                     for (int n = 0; n < 2; ++n) acc[ai][bj][m][n] = acc[ai][bj][m][n] * r; }
;     ...
;             for (int n = 0; n < 2; ++n) { const int ch = bj * 2816 + fbase + 4 * n;
;                 const f32x4 w0 = *(const f32x4*)(cw + ch), w1 = *(const f32x4*)(cw + 5632 + ch), w2 = *(const f32x4*)(cw + 2 * 5632 + ch), bb = *(const f32x4*)(cb + ch);
; #pragma unroll
;                 for (int ai = 0; ai < 2; ++ai) { const int kb = 2 * ai + wr;
;                     f32x4 c62 = (f32x4){0.f, 0.f, 0.f, 0.f}, c63 = c62;
;                     if (kb > 0) { c62 = *(const PG8_LAS f32x4*)(exch + (((kb - 1) * 2 + 0) * 256 + bj * HALF + 32 * wc + 8 * fq + 4 * n)); c63 = *(const PG8_LAS f32x4*)(exch + (((kb - 1) * 2 + 1) * 256 + bj * HALF + 32 * wc + 8 * fq + 4 * n)); }
; #pragma unroll
;                     for (int m = 3; m >= 0; --m) { f32x4 cur = acc[ai][bj][m][n], res;
; #pragma unroll
;                         for (int j = 0; j < 4; ++j) { const float c = cur[j]; const float pv = (m > 0) ? acc[ai][bj][m > 0 ? m - 1 : 0][n][j] : (fr == 15 ? c63[j] : c62[j]); float t1, t2;
;                             asm volatile("s_nop 1\n\tv_mov_b32_dpp %0, %3 row_ror:1 row_mask:0xf bank_mask:0xf\n\tv_mov_b32_dpp %1, %3 row_ror:2 row_mask:0xf bank_mask:0xf\n\t"
;                                          "v_mov_b32_dpp %0, %2 row_shr:1 row_mask:0xf bank_mask:0xf\n\tv_mov_b32_dpp %1, %2 row_shr:2 row_mask:0xf bank_mask:0xf"
;                                          : "=&v"(t1), "=&v"(t2) : "v"(c), "v"(pv));
;                             res[j] = bb[j] + w0[j] * t2 + w1[j] * t1 + w2[j] * c; }
;                         asm volatile("" : "+v"(res[0]), "+v"(res[1]), "+v"(res[2]), "+v"(res[3]));
;                         acc[ai][bj][m][n] = res; } }
.LBB0_1192:
	v_mov_b32_e32 v30, v192
	v_mov_b32_e32 v31, v192
	v_pk_mul_f32 v[30:31], v[68:69], v[30:31]
	v_mov_b32_e32 v68, v190
	v_mov_b32_e32 v69, v190
	v_mov_b32_e32 v189, v188
	v_pk_mul_f32 v[64:65], v[64:65], v[68:69]
	v_mov_b32_e32 v68, v188
	v_mov_b32_e32 v69, v188
	v_pk_mul_f32 v[56:57], v[56:57], v[68:69]
	v_pk_mul_f32 v[54:55], v[54:55], v[188:189]
	v_mov_b32_e32 v191, v190
	v_pk_mul_f32 v[62:63], v[62:63], v[190:191]
	v_mov_b32_e32 v112, v46
	v_fmac_f32_dpp v112, v114, v90 row_shr:2 row_mask:0xf bank_mask:0xf
	v_fmac_f32_dpp v112, v54, v90 row_shl:14 row_mask:0xf bank_mask:0xf
	v_fmac_f32_dpp v112, v114, v102 row_shr:1 row_mask:0xf bank_mask:0xf
	v_fmac_f32_dpp v112, v54, v102 row_shl:15 row_mask:0xf bank_mask:0xf
	v_fmac_f32_e32 v112, v114, v94
	v_mov_b32_e32 v110, v47
	v_fmac_f32_dpp v110, v115, v91 row_shr:2 row_mask:0xf bank_mask:0xf
	v_fmac_f32_dpp v110, v55, v91 row_shl:14 row_mask:0xf bank_mask:0xf
	v_fmac_f32_dpp v110, v115, v103 row_shr:1 row_mask:0xf bank_mask:0xf
	v_fmac_f32_dpp v110, v55, v103 row_shl:15 row_mask:0xf bank_mask:0xf
	v_fmac_f32_e32 v110, v115, v95
	v_mov_b32_e32 v111, v48
	v_fmac_f32_dpp v111, v116, v92 row_shr:2 row_mask:0xf bank_mask:0xf
	v_fmac_f32_dpp v111, v56, v92 row_shl:14 row_mask:0xf bank_mask:0xf
	v_fmac_f32_dpp v111, v116, v104 row_shr:1 row_mask:0xf bank_mask:0xf
	v_fmac_f32_dpp v111, v56, v104 row_shl:15 row_mask:0xf bank_mask:0xf
	v_fmac_f32_e32 v111, v116, v96
	v_mov_b32_e32 v113, v49
	v_fmac_f32_dpp v113, v117, v93 row_shr:2 row_mask:0xf bank_mask:0xf
	v_fmac_f32_dpp v113, v57, v93 row_shl:14 row_mask:0xf bank_mask:0xf
	v_fmac_f32_dpp v113, v117, v105 row_shr:1 row_mask:0xf bank_mask:0xf
	v_fmac_f32_dpp v113, v57, v105 row_shl:15 row_mask:0xf bank_mask:0xf
	v_fmac_f32_e32 v113, v117, v97
	v_mov_b32_e32 v193, v192
	v_mov_b32_e32 v116, v46
	v_fmac_f32_dpp v116, v54, v90 row_shr:2 row_mask:0xf bank_mask:0xf
	v_fmac_f32_dpp v116, v62, v90 row_shl:14 row_mask:0xf bank_mask:0xf
	v_fmac_f32_dpp v116, v54, v102 row_shr:1 row_mask:0xf bank_mask:0xf
	v_fmac_f32_dpp v116, v62, v102 row_shl:15 row_mask:0xf bank_mask:0xf
	v_fmac_f32_e32 v116, v54, v94
	v_pk_mul_f32 v[66:67], v[66:67], v[192:193]
	v_mov_b32_e32 v114, v47
	v_fmac_f32_dpp v114, v55, v91 row_shr:2 row_mask:0xf bank_mask:0xf
	v_fmac_f32_dpp v114, v63, v91 row_shl:14 row_mask:0xf bank_mask:0xf
	v_fmac_f32_dpp v114, v55, v103 row_shr:1 row_mask:0xf bank_mask:0xf
	v_fmac_f32_dpp v114, v63, v103 row_shl:15 row_mask:0xf bank_mask:0xf
	v_fmac_f32_e32 v114, v55, v95
	s_movk_i32 s0, 0x2000
	v_mov_b32_e32 v115, v48
	v_fmac_f32_dpp v115, v56, v92 row_shr:2 row_mask:0xf bank_mask:0xf
	v_fmac_f32_dpp v115, v64, v92 row_shl:14 row_mask:0xf bank_mask:0xf
	v_fmac_f32_dpp v115, v56, v104 row_shr:1 row_mask:0xf bank_mask:0xf
	v_fmac_f32_dpp v115, v64, v104 row_shl:15 row_mask:0xf bank_mask:0xf
	v_fmac_f32_e32 v115, v56, v96
	v_mov_b32_e32 v117, v49
	v_fmac_f32_dpp v117, v57, v93 row_shr:2 row_mask:0xf bank_mask:0xf
	v_fmac_f32_dpp v117, v65, v93 row_shl:14 row_mask:0xf bank_mask:0xf
	v_fmac_f32_dpp v117, v57, v105 row_shr:1 row_mask:0xf bank_mask:0xf
	v_fmac_f32_dpp v117, v65, v105 row_shl:15 row_mask:0xf bank_mask:0xf
	v_fmac_f32_e32 v117, v57, v97
	s_waitcnt lgkmcnt(0)
	v_cndmask_b32_e64 v57, v106, v74, s[8:9]
	v_mov_b32_e32 v120, v46
	v_fmac_f32_dpp v120, v62, v90 row_shr:2 row_mask:0xf bank_mask:0xf
	v_fmac_f32_dpp v120, v66, v90 row_shl:14 row_mask:0xf bank_mask:0xf
	v_fmac_f32_dpp v120, v62, v102 row_shr:1 row_mask:0xf bank_mask:0xf
	v_fmac_f32_dpp v120, v66, v102 row_shl:15 row_mask:0xf bank_mask:0xf
	v_fmac_f32_e32 v120, v62, v94
	v_mov_b32_e32 v118, v47
	v_fmac_f32_dpp v118, v63, v91 row_shr:2 row_mask:0xf bank_mask:0xf
	v_fmac_f32_dpp v118, v67, v91 row_shl:14 row_mask:0xf bank_mask:0xf
	v_fmac_f32_dpp v118, v63, v103 row_shr:1 row_mask:0xf bank_mask:0xf
	v_fmac_f32_dpp v118, v67, v103 row_shl:15 row_mask:0xf bank_mask:0xf
	v_fmac_f32_e32 v118, v63, v95
	v_mov_b32_e32 v119, v48
	v_fmac_f32_dpp v119, v64, v92 row_shr:2 row_mask:0xf bank_mask:0xf
	v_fmac_f32_dpp v119, v30, v92 row_shl:14 row_mask:0xf bank_mask:0xf
	v_fmac_f32_dpp v119, v64, v104 row_shr:1 row_mask:0xf bank_mask:0xf
	v_fmac_f32_dpp v119, v30, v104 row_shl:15 row_mask:0xf bank_mask:0xf
	v_fmac_f32_e32 v119, v64, v96
	v_mov_b32_e32 v121, v49
	v_fmac_f32_dpp v121, v65, v93 row_shr:2 row_mask:0xf bank_mask:0xf
	v_fmac_f32_dpp v121, v31, v93 row_shl:14 row_mask:0xf bank_mask:0xf
	v_fmac_f32_dpp v121, v65, v105 row_shr:1 row_mask:0xf bank_mask:0xf
	v_fmac_f32_dpp v121, v31, v105 row_shl:15 row_mask:0xf bank_mask:0xf
	v_fmac_f32_e32 v121, v65, v97
	v_cndmask_b32_e64 v56, v107, v75, s[8:9]
	v_mov_b32_e32 v106, v46
	v_fmac_f32_dpp v106, v66, v90 row_shr:2 row_mask:0xf bank_mask:0xf
	v_fmac_f32_dpp v106, v57, v90 row_shl:14 row_mask:0xf bank_mask:0xf
	v_fmac_f32_dpp v106, v66, v102 row_shr:1 row_mask:0xf bank_mask:0xf
	v_fmac_f32_dpp v106, v57, v102 row_shl:15 row_mask:0xf bank_mask:0xf
	v_cndmask_b32_e64 v55, v108, v76, s[8:9]
	v_mov_b32_e32 v102, v47
	v_fmac_f32_dpp v102, v67, v91 row_shr:2 row_mask:0xf bank_mask:0xf
	v_fmac_f32_dpp v102, v56, v91 row_shl:14 row_mask:0xf bank_mask:0xf
	v_fmac_f32_dpp v102, v67, v103 row_shr:1 row_mask:0xf bank_mask:0xf
	v_fmac_f32_dpp v102, v56, v103 row_shl:15 row_mask:0xf bank_mask:0xf
	s_nop 1
	v_mov_b32_dpp v46, v55 row_ror:1 row_mask:0xf bank_mask:0xf
	v_mov_b32_dpp v47, v55 row_ror:2 row_mask:0xf bank_mask:0xf
	v_mov_b32_dpp v46, v30 row_shr:1 row_mask:0xf bank_mask:0xf
	v_mov_b32_dpp v47, v30 row_shr:2 row_mask:0xf bank_mask:0xf
	v_cndmask_b32_e64 v54, v109, v77, s[8:9]
	v_fma_f32 v48, v92, v47, v48
	v_fmac_f32_e32 v48, v104, v46
	v_fmac_f32_e32 v48, v30, v96
	s_nop 1
	v_mov_b32_dpp v30, v54 row_ror:1 row_mask:0xf bank_mask:0xf
	v_mov_b32_dpp v46, v54 row_ror:2 row_mask:0xf bank_mask:0xf
	v_mov_b32_dpp v30, v31 row_shr:1 row_mask:0xf bank_mask:0xf
	v_mov_b32_dpp v46, v31 row_shr:2 row_mask:0xf bank_mask:0xf
	v_fmac_f32_e32 v106, v66, v94
	v_fmac_f32_e32 v49, v93, v46
	v_fmac_f32_e32 v49, v105, v30
	v_add_co_u32_e32 v30, vcc, s0, v204
	v_fmac_f32_e32 v49, v31, v97
	s_nop 0
	v_addc_co_u32_e32 v31, vcc, 0, v205, vcc
	v_add_co_u32_e32 v46, vcc, s0, v202
	v_fmac_f32_e32 v102, v67, v95
	s_nop 0
	v_addc_co_u32_e32 v47, vcc, 0, v203, vcc
	v_add_co_u32_e32 v54, vcc, 0x2000, v200
	global_load_dwordx4 v[62:65], v[30:31], off offset:3072
	global_load_dwordx4 v[66:69], v[46:47], off offset:3072
	v_addc_co_u32_e32 v55, vcc, 0, v201, vcc
	global_load_dwordx4 v[74:77], v[54:55], off offset:3072
	v_add_co_u32_e32 v54, vcc, 0x2000, v198
	v_mov_b32_e32 v78, 0
	s_nop 0
	v_addc_co_u32_e32 v55, vcc, 0, v199, vcc
	global_load_dwordx4 v[54:57], v[54:55], off offset:3072
	s_and_b64 vcc, exec, s[10:11]
	v_mov_b32_e32 v90, 0
	v_mov_b32_e32 v91, 0
	v_mov_b32_e32 v92, 0
	v_mov_b32_e32 v93, 0
	v_mov_b32_e32 v94, 0
	v_mov_b32_e32 v95, 0
	v_mov_b32_e32 v96, 0
	v_mov_b32_e32 v97, 0
	s_cbranch_vccnz .LBB0_1194
	v_add_u32_e32 v80, s43, v228
	v_add_u32_e32 v79, s30, v228
	ds_read_b128 v[90:93], v80
	ds_read_b128 v[94:97], v79
; #define PG8_LAS __attribute__((address_space(3)))
;     __device__ __forceinline__ void operator()(f32x4 (&acc)[2][2][4][2], const Unit& u, int ui, int wr, int wc, int fr_, int fq_) const {
;     ...
;             for (int m = 0; m < 4; ++m) { const float r = rtab[ui * 256 + ai * HALF + wr * 64 + m * 16 + fr];
; #pragma unroll
;                 for (int bj = 0; bj < 2; ++bj)
; #pragma unroll
;                     for (int n = 0; n < 2; ++n) acc[ai][bj][m][n] = acc[ai][bj][m][n] * r; }
;     ...
;             for (int n = 0; n < 2; ++n) { const int ch = bj * 2816 + fbase + 4 * n;
;                 const f32x4 w0 = *(const f32x4*)(cw + ch), w1 = *(const f32x4*)(cw + 5632 + ch), w2 = *(const f32x4*)(cw + 2 * 5632 + ch), bb = *(const f32x4*)(cb + ch);
; #pragma unroll
;                 for (int ai = 0; ai < 2; ++ai) { const int kb = 2 * ai + wr;
;                     f32x4 c62 = (f32x4){0.f, 0.f, 0.f, 0.f}, c63 = c62;
;                     if (kb > 0) { c62 = *(const PG8_LAS f32x4*)(exch + (((kb - 1) * 2 + 0) * 256 + bj * HALF + 32 * wc + 8 * fq + 4 * n)); c63 = *(const PG8_LAS f32x4*)(exch + (((kb - 1) * 2 + 1) * 256 + bj * HALF + 32 * wc + 8 * fq + 4 * n)); }
; #pragma unroll
;                     for (int m = 3; m >= 0; --m) { f32x4 cur = acc[ai][bj][m][n], res;
; #pragma unroll
;                         for (int j = 0; j < 4; ++j) { const float c = cur[j]; const float pv = (m > 0) ? acc[ai][bj][m > 0 ? m - 1 : 0][n][j] : (fr == 15 ? c63[j] : c62[j]); float t1, t2;
;                             asm volatile("s_nop 1\n\tv_mov_b32_dpp %0, %3 row_ror:1 row_mask:0xf bank_mask:0xf\n\tv_mov_b32_dpp %1, %3 row_ror:2 row_mask:0xf bank_mask:0xf\n\t"
;                                          "v_mov_b32_dpp %0, %2 row_shr:1 row_mask:0xf bank_mask:0xf\n\tv_mov_b32_dpp %1, %2 row_shr:2 row_mask:0xf bank_mask:0xf"
;                                          : "=&v"(t1), "=&v"(t2) : "v"(c), "v"(pv));
;                             res[j] = bb[j] + w0[j] * t2 + w1[j] * t1 + w2[j] * c; }
;                         asm volatile("" : "+v"(res[0]), "+v"(res[1]), "+v"(res[2]), "+v"(res[3]));
;                         acc[ai][bj][m][n] = res; } }
.LBB0_1194:
	v_mov_b32_e32 v80, v194
	v_mov_b32_e32 v81, v194
	v_pk_mul_f32 v[44:45], v[44:45], v[80:81]
	v_mov_b32_e32 v80, v196
	v_mov_b32_e32 v81, v196
	v_pk_mul_f32 v[40:41], v[40:41], v[80:81]
	v_pk_mul_f32 v[38:39], v[38:39], v[196:197]
	v_pk_mul_f32 v[42:43], v[42:43], v[194:195]
	s_and_b64 vcc, exec, s[12:13]
	s_waitcnt vmcnt(0)
	v_mov_b32_e32 v104, v54
	v_fmac_f32_dpp v104, v98, v62 row_shr:2 row_mask:0xf bank_mask:0xf
	v_fmac_f32_dpp v104, v38, v62 row_shl:14 row_mask:0xf bank_mask:0xf
	v_fmac_f32_dpp v104, v98, v66 row_shr:1 row_mask:0xf bank_mask:0xf
	v_fmac_f32_dpp v104, v38, v66 row_shl:15 row_mask:0xf bank_mask:0xf
	v_fmac_f32_e32 v104, v98, v74
	v_mov_b32_e32 v103, v55
	v_fmac_f32_dpp v103, v99, v63 row_shr:2 row_mask:0xf bank_mask:0xf
	v_fmac_f32_dpp v103, v39, v63 row_shl:14 row_mask:0xf bank_mask:0xf
	v_fmac_f32_dpp v103, v99, v67 row_shr:1 row_mask:0xf bank_mask:0xf
	v_fmac_f32_dpp v103, v39, v67 row_shl:15 row_mask:0xf bank_mask:0xf
	v_fmac_f32_e32 v103, v99, v75
	v_mov_b32_e32 v98, v56
	v_fmac_f32_dpp v98, v100, v64 row_shr:2 row_mask:0xf bank_mask:0xf
	v_fmac_f32_dpp v98, v40, v64 row_shl:14 row_mask:0xf bank_mask:0xf
	v_fmac_f32_dpp v98, v100, v68 row_shr:1 row_mask:0xf bank_mask:0xf
	v_fmac_f32_dpp v98, v40, v68 row_shl:15 row_mask:0xf bank_mask:0xf
	v_fmac_f32_e32 v98, v100, v76
	v_mov_b32_e32 v99, v57
	v_fmac_f32_dpp v99, v101, v65 row_shr:2 row_mask:0xf bank_mask:0xf
	v_fmac_f32_dpp v99, v41, v65 row_shl:14 row_mask:0xf bank_mask:0xf
	v_fmac_f32_dpp v99, v101, v69 row_shr:1 row_mask:0xf bank_mask:0xf
	v_fmac_f32_dpp v99, v41, v69 row_shl:15 row_mask:0xf bank_mask:0xf
	v_fmac_f32_e32 v99, v101, v77
	v_mov_b32_e32 v81, 0
	v_mov_b32_e32 v107, v54
	v_fmac_f32_dpp v107, v38, v62 row_shr:2 row_mask:0xf bank_mask:0xf
	v_fmac_f32_dpp v107, v42, v62 row_shl:14 row_mask:0xf bank_mask:0xf
	v_fmac_f32_dpp v107, v38, v66 row_shr:1 row_mask:0xf bank_mask:0xf
	v_fmac_f32_dpp v107, v42, v66 row_shl:15 row_mask:0xf bank_mask:0xf
	v_fmac_f32_e32 v107, v38, v74
	v_mov_b32_e32 v80, 0
	v_mov_b32_e32 v105, v55
	v_fmac_f32_dpp v105, v39, v63 row_shr:2 row_mask:0xf bank_mask:0xf
	v_fmac_f32_dpp v105, v43, v63 row_shl:14 row_mask:0xf bank_mask:0xf
	v_fmac_f32_dpp v105, v39, v67 row_shr:1 row_mask:0xf bank_mask:0xf
	v_fmac_f32_dpp v105, v43, v67 row_shl:15 row_mask:0xf bank_mask:0xf
	v_fmac_f32_e32 v105, v39, v75
	v_mov_b32_e32 v79, 0
	v_mov_b32_e32 v100, v56
	v_fmac_f32_dpp v100, v40, v64 row_shr:2 row_mask:0xf bank_mask:0xf
	v_fmac_f32_dpp v100, v44, v64 row_shl:14 row_mask:0xf bank_mask:0xf
	v_fmac_f32_dpp v100, v40, v68 row_shr:1 row_mask:0xf bank_mask:0xf
	v_fmac_f32_dpp v100, v44, v68 row_shl:15 row_mask:0xf bank_mask:0xf
	v_fmac_f32_e32 v100, v40, v76
	v_mov_b32_e32 v101, v57
	v_fmac_f32_dpp v101, v41, v65 row_shr:2 row_mask:0xf bank_mask:0xf
	v_fmac_f32_dpp v101, v45, v65 row_shl:14 row_mask:0xf bank_mask:0xf
	v_fmac_f32_dpp v101, v41, v69 row_shr:1 row_mask:0xf bank_mask:0xf
	v_fmac_f32_dpp v101, v45, v69 row_shl:15 row_mask:0xf bank_mask:0xf
	v_fmac_f32_e32 v101, v41, v77
	s_waitcnt lgkmcnt(0)
	v_cndmask_b32_e64 v41, v90, v94, s[8:9]
	v_mov_b32_e32 v127, v54
	v_fmac_f32_dpp v127, v42, v62 row_shr:2 row_mask:0xf bank_mask:0xf
	v_fmac_f32_dpp v127, v86, v62 row_shl:14 row_mask:0xf bank_mask:0xf
	v_fmac_f32_dpp v127, v42, v66 row_shr:1 row_mask:0xf bank_mask:0xf
	v_fmac_f32_dpp v127, v86, v66 row_shl:15 row_mask:0xf bank_mask:0xf
	v_fmac_f32_e32 v127, v42, v74
	v_mov_b32_e32 v125, v55
	v_fmac_f32_dpp v125, v43, v63 row_shr:2 row_mask:0xf bank_mask:0xf
	v_fmac_f32_dpp v125, v87, v63 row_shl:14 row_mask:0xf bank_mask:0xf
	v_fmac_f32_dpp v125, v43, v67 row_shr:1 row_mask:0xf bank_mask:0xf
	v_fmac_f32_dpp v125, v87, v67 row_shl:15 row_mask:0xf bank_mask:0xf
	v_fmac_f32_e32 v125, v43, v75
	v_mov_b32_e32 v108, v56
	v_fmac_f32_dpp v108, v44, v64 row_shr:2 row_mask:0xf bank_mask:0xf
	v_fmac_f32_dpp v108, v88, v64 row_shl:14 row_mask:0xf bank_mask:0xf
	v_fmac_f32_dpp v108, v44, v68 row_shr:1 row_mask:0xf bank_mask:0xf
	v_fmac_f32_dpp v108, v88, v68 row_shl:15 row_mask:0xf bank_mask:0xf
	v_fmac_f32_e32 v108, v44, v76
	v_mov_b32_e32 v109, v57
	v_fmac_f32_dpp v109, v45, v65 row_shr:2 row_mask:0xf bank_mask:0xf
	v_fmac_f32_dpp v109, v89, v65 row_shl:14 row_mask:0xf bank_mask:0xf
	v_fmac_f32_dpp v109, v45, v69 row_shr:1 row_mask:0xf bank_mask:0xf
	v_fmac_f32_dpp v109, v89, v69 row_shl:15 row_mask:0xf bank_mask:0xf
	v_fmac_f32_e32 v109, v45, v77
	v_cndmask_b32_e64 v38, v93, v97, s[8:9]
	v_cndmask_b32_e64 v39, v92, v96, s[8:9]
	v_mov_b32_e32 v97, v54
	v_fmac_f32_dpp v97, v86, v62 row_shr:2 row_mask:0xf bank_mask:0xf
	v_fmac_f32_dpp v97, v41, v62 row_shl:14 row_mask:0xf bank_mask:0xf
	v_fmac_f32_dpp v97, v86, v66 row_shr:1 row_mask:0xf bank_mask:0xf
	v_fmac_f32_dpp v97, v41, v66 row_shl:15 row_mask:0xf bank_mask:0xf
	v_cndmask_b32_e64 v40, v91, v95, s[8:9]
	v_fmac_f32_e32 v97, v86, v74
	v_mov_b32_e32 v96, v55
	v_fmac_f32_dpp v96, v87, v63 row_shr:2 row_mask:0xf bank_mask:0xf
	v_fmac_f32_dpp v96, v40, v63 row_shl:14 row_mask:0xf bank_mask:0xf
	v_fmac_f32_dpp v96, v87, v67 row_shr:1 row_mask:0xf bank_mask:0xf
	v_fmac_f32_dpp v96, v40, v67 row_shl:15 row_mask:0xf bank_mask:0xf
	v_fmac_f32_e32 v96, v87, v75
	v_mov_b32_e32 v95, v56
	v_fmac_f32_dpp v95, v88, v64 row_shr:2 row_mask:0xf bank_mask:0xf
	v_fmac_f32_dpp v95, v39, v64 row_shl:14 row_mask:0xf bank_mask:0xf
	v_fmac_f32_dpp v95, v88, v68 row_shr:1 row_mask:0xf bank_mask:0xf
	v_fmac_f32_dpp v95, v39, v68 row_shl:15 row_mask:0xf bank_mask:0xf
	v_fmac_f32_e32 v95, v88, v76
	v_mov_b32_e32 v94, v57
	v_fmac_f32_dpp v94, v89, v65 row_shr:2 row_mask:0xf bank_mask:0xf
	v_fmac_f32_dpp v94, v38, v65 row_shl:14 row_mask:0xf bank_mask:0xf
	v_fmac_f32_dpp v94, v89, v69 row_shr:1 row_mask:0xf bank_mask:0xf
	v_fmac_f32_dpp v94, v38, v69 row_shl:15 row_mask:0xf bank_mask:0xf
	v_fmac_f32_e32 v94, v89, v77
	v_mov_b32_e32 v38, 0
	v_mov_b32_e32 v39, 0
	v_mov_b32_e32 v40, 0
	v_mov_b32_e32 v41, 0
	s_cbranch_vccnz .LBB0_1196
	ds_read_b128 v[78:81], v227 offset:2560
	ds_read_b128 v[38:41], v227 offset:3584
; #define PG8_LAS __attribute__((address_space(3)))
;     __device__ __forceinline__ void operator()(f32x4 (&acc)[2][2][4][2], const Unit& u, int ui, int wr, int wc, int fr_, int fq_) const {
;     ...
;             for (int m = 0; m < 4; ++m) { const float r = rtab[ui * 256 + ai * HALF + wr * 64 + m * 16 + fr];
; #pragma unroll
;                 for (int bj = 0; bj < 2; ++bj)
; #pragma unroll
;                     for (int n = 0; n < 2; ++n) acc[ai][bj][m][n] = acc[ai][bj][m][n] * r; }
;     ...
;             for (int n = 0; n < 2; ++n) { const int ch = bj * 2816 + fbase + 4 * n;
;                 const f32x4 w0 = *(const f32x4*)(cw + ch), w1 = *(const f32x4*)(cw + 5632 + ch), w2 = *(const f32x4*)(cw + 2 * 5632 + ch), bb = *(const f32x4*)(cb + ch);
; #pragma unroll
;                 for (int ai = 0; ai < 2; ++ai) { const int kb = 2 * ai + wr;
;                     f32x4 c62 = (f32x4){0.f, 0.f, 0.f, 0.f}, c63 = c62;
;                     if (kb > 0) { c62 = *(const PG8_LAS f32x4*)(exch + (((kb - 1) * 2 + 0) * 256 + bj * HALF + 32 * wc + 8 * fq + 4 * n)); c63 = *(const PG8_LAS f32x4*)(exch + (((kb - 1) * 2 + 1) * 256 + bj * HALF + 32 * wc + 8 * fq + 4 * n)); }
; #pragma unroll
;                     for (int m = 3; m >= 0; --m) { f32x4 cur = acc[ai][bj][m][n], res;
; #pragma unroll
;                         for (int j = 0; j < 4; ++j) { const float c = cur[j]; const float pv = (m > 0) ? acc[ai][bj][m > 0 ? m - 1 : 0][n][j] : (fr == 15 ? c63[j] : c62[j]); float t1, t2;
;                             asm volatile("s_nop 1\n\tv_mov_b32_dpp %0, %3 row_ror:1 row_mask:0xf bank_mask:0xf\n\tv_mov_b32_dpp %1, %3 row_ror:2 row_mask:0xf bank_mask:0xf\n\t"
;                                          "v_mov_b32_dpp %0, %2 row_shr:1 row_mask:0xf bank_mask:0xf\n\tv_mov_b32_dpp %1, %2 row_shr:2 row_mask:0xf bank_mask:0xf"
;                                          : "=&v"(t1), "=&v"(t2) : "v"(c), "v"(pv));
;                             res[j] = bb[j] + w0[j] * t2 + w1[j] * t1 + w2[j] * c; }
;                         asm volatile("" : "+v"(res[0]), "+v"(res[1]), "+v"(res[2]), "+v"(res[3]));
;                         acc[ai][bj][m][n] = res; } }
.LBB0_1196:
	v_mov_b32_e32 v42, v192
	v_mov_b32_e32 v43, v192
	v_pk_mul_f32 v[36:37], v[36:37], v[42:43]
	v_mov_b32_e32 v42, v190
	v_mov_b32_e32 v43, v190
	v_pk_mul_f32 v[28:29], v[28:29], v[42:43]
	v_mov_b32_e32 v42, v188
	v_mov_b32_e32 v43, v188
	v_pk_mul_f32 v[24:25], v[24:25], v[42:43]
	v_pk_mul_f32 v[22:23], v[22:23], v[188:189]
	v_pk_mul_f32 v[26:27], v[26:27], v[190:191]
	v_pk_mul_f32 v[34:35], v[34:35], v[192:193]
	v_mov_b32_e32 v87, v54
	v_fmac_f32_dpp v87, v82, v62 row_shr:2 row_mask:0xf bank_mask:0xf
	v_fmac_f32_dpp v87, v22, v62 row_shl:14 row_mask:0xf bank_mask:0xf
	v_fmac_f32_dpp v87, v82, v66 row_shr:1 row_mask:0xf bank_mask:0xf
	v_fmac_f32_dpp v87, v22, v66 row_shl:15 row_mask:0xf bank_mask:0xf
	v_fmac_f32_e32 v87, v82, v74
	v_mov_b32_e32 v86, v55
	v_fmac_f32_dpp v86, v83, v63 row_shr:2 row_mask:0xf bank_mask:0xf
	v_fmac_f32_dpp v86, v23, v63 row_shl:14 row_mask:0xf bank_mask:0xf
	v_fmac_f32_dpp v86, v83, v67 row_shr:1 row_mask:0xf bank_mask:0xf
	v_fmac_f32_dpp v86, v23, v67 row_shl:15 row_mask:0xf bank_mask:0xf
	v_fmac_f32_e32 v86, v83, v75
	v_mov_b32_e32 v82, v56
	v_fmac_f32_dpp v82, v84, v64 row_shr:2 row_mask:0xf bank_mask:0xf
	v_fmac_f32_dpp v82, v24, v64 row_shl:14 row_mask:0xf bank_mask:0xf
	v_fmac_f32_dpp v82, v84, v68 row_shr:1 row_mask:0xf bank_mask:0xf
	v_fmac_f32_dpp v82, v24, v68 row_shl:15 row_mask:0xf bank_mask:0xf
	v_fmac_f32_e32 v82, v84, v76
	v_mov_b32_e32 v83, v57
	v_fmac_f32_dpp v83, v85, v65 row_shr:2 row_mask:0xf bank_mask:0xf
	v_fmac_f32_dpp v83, v25, v65 row_shl:14 row_mask:0xf bank_mask:0xf
	v_fmac_f32_dpp v83, v85, v69 row_shr:1 row_mask:0xf bank_mask:0xf
	v_fmac_f32_dpp v83, v25, v69 row_shl:15 row_mask:0xf bank_mask:0xf
	v_fmac_f32_e32 v83, v85, v77
	v_mov_b32_e32 v44, 0
	v_mov_b32_e32 v89, v54
	v_fmac_f32_dpp v89, v22, v62 row_shr:2 row_mask:0xf bank_mask:0xf
	v_fmac_f32_dpp v89, v26, v62 row_shl:14 row_mask:0xf bank_mask:0xf
	v_fmac_f32_dpp v89, v22, v66 row_shr:1 row_mask:0xf bank_mask:0xf
	v_fmac_f32_dpp v89, v26, v66 row_shl:15 row_mask:0xf bank_mask:0xf
	v_fmac_f32_e32 v89, v22, v74
	v_mov_b32_e32 v45, 0
	v_mov_b32_e32 v88, v55
	v_fmac_f32_dpp v88, v23, v63 row_shr:2 row_mask:0xf bank_mask:0xf
	v_fmac_f32_dpp v88, v27, v63 row_shl:14 row_mask:0xf bank_mask:0xf
	v_fmac_f32_dpp v88, v23, v67 row_shr:1 row_mask:0xf bank_mask:0xf
	v_fmac_f32_dpp v88, v27, v67 row_shl:15 row_mask:0xf bank_mask:0xf
	v_fmac_f32_e32 v88, v23, v75
	v_mov_b32_e32 v42, 0
	v_mov_b32_e32 v84, v56
	v_fmac_f32_dpp v84, v24, v64 row_shr:2 row_mask:0xf bank_mask:0xf
	v_fmac_f32_dpp v84, v28, v64 row_shl:14 row_mask:0xf bank_mask:0xf
	v_fmac_f32_dpp v84, v24, v68 row_shr:1 row_mask:0xf bank_mask:0xf
	v_fmac_f32_dpp v84, v28, v68 row_shl:15 row_mask:0xf bank_mask:0xf
	v_fmac_f32_e32 v84, v24, v76
	v_mov_b32_e32 v85, v57
	v_fmac_f32_dpp v85, v25, v65 row_shr:2 row_mask:0xf bank_mask:0xf
	v_fmac_f32_dpp v85, v29, v65 row_shl:14 row_mask:0xf bank_mask:0xf
	v_fmac_f32_dpp v85, v25, v69 row_shr:1 row_mask:0xf bank_mask:0xf
	v_fmac_f32_dpp v85, v29, v69 row_shl:15 row_mask:0xf bank_mask:0xf
	v_fmac_f32_e32 v85, v25, v77
	s_waitcnt lgkmcnt(0)
	v_cndmask_b32_e64 v25, v78, v38, s[8:9]
	v_mov_b32_e32 v93, v54
	v_fmac_f32_dpp v93, v26, v62 row_shr:2 row_mask:0xf bank_mask:0xf
	v_fmac_f32_dpp v93, v34, v62 row_shl:14 row_mask:0xf bank_mask:0xf
	v_fmac_f32_dpp v93, v26, v66 row_shr:1 row_mask:0xf bank_mask:0xf
	v_fmac_f32_dpp v93, v34, v66 row_shl:15 row_mask:0xf bank_mask:0xf
	v_fmac_f32_e32 v93, v26, v74
	v_mov_b32_e32 v92, v55
	v_fmac_f32_dpp v92, v27, v63 row_shr:2 row_mask:0xf bank_mask:0xf
	v_fmac_f32_dpp v92, v35, v63 row_shl:14 row_mask:0xf bank_mask:0xf
	v_fmac_f32_dpp v92, v27, v67 row_shr:1 row_mask:0xf bank_mask:0xf
	v_fmac_f32_dpp v92, v35, v67 row_shl:15 row_mask:0xf bank_mask:0xf
	v_fmac_f32_e32 v92, v27, v75
	v_mov_b32_e32 v90, v56
	v_fmac_f32_dpp v90, v28, v64 row_shr:2 row_mask:0xf bank_mask:0xf
	v_fmac_f32_dpp v90, v36, v64 row_shl:14 row_mask:0xf bank_mask:0xf
	v_fmac_f32_dpp v90, v28, v68 row_shr:1 row_mask:0xf bank_mask:0xf
	v_fmac_f32_dpp v90, v36, v68 row_shl:15 row_mask:0xf bank_mask:0xf
	v_fmac_f32_e32 v90, v28, v76
	v_mov_b32_e32 v91, v57
	v_fmac_f32_dpp v91, v29, v65 row_shr:2 row_mask:0xf bank_mask:0xf
	v_fmac_f32_dpp v91, v37, v65 row_shl:14 row_mask:0xf bank_mask:0xf
	v_fmac_f32_dpp v91, v29, v69 row_shr:1 row_mask:0xf bank_mask:0xf
	v_fmac_f32_dpp v91, v37, v69 row_shl:15 row_mask:0xf bank_mask:0xf
	v_fmac_f32_e32 v91, v29, v77
	v_cndmask_b32_e64 v24, v79, v39, s[8:9]
	v_mov_b32_e32 v78, v54
	v_fmac_f32_dpp v78, v34, v62 row_shr:2 row_mask:0xf bank_mask:0xf
	v_fmac_f32_dpp v78, v25, v62 row_shl:14 row_mask:0xf bank_mask:0xf
	v_fmac_f32_dpp v78, v34, v66 row_shr:1 row_mask:0xf bank_mask:0xf
	v_fmac_f32_dpp v78, v25, v66 row_shl:15 row_mask:0xf bank_mask:0xf
	s_nop 1
	v_mov_b32_dpp v25, v24 row_ror:1 row_mask:0xf bank_mask:0xf
	v_mov_b32_dpp v26, v24 row_ror:2 row_mask:0xf bank_mask:0xf
	v_mov_b32_dpp v25, v35 row_shr:1 row_mask:0xf bank_mask:0xf
	v_mov_b32_dpp v26, v35 row_shr:2 row_mask:0xf bank_mask:0xf
	v_cndmask_b32_e64 v23, v80, v40, s[8:9]
	v_fma_f32 v55, v63, v26, v55
	v_fmac_f32_e32 v55, v67, v25
	v_cndmask_b32_e64 v22, v81, v41, s[8:9]
	v_mov_b32_e32 v54, v56
	v_fmac_f32_dpp v54, v36, v64 row_shr:2 row_mask:0xf bank_mask:0xf
	v_fmac_f32_dpp v54, v23, v64 row_shl:14 row_mask:0xf bank_mask:0xf
	v_fmac_f32_dpp v54, v36, v68 row_shr:1 row_mask:0xf bank_mask:0xf
	v_fmac_f32_dpp v54, v23, v68 row_shl:15 row_mask:0xf bank_mask:0xf
	s_nop 1
	v_mov_b32_dpp v23, v22 row_ror:1 row_mask:0xf bank_mask:0xf
	v_mov_b32_dpp v24, v22 row_ror:2 row_mask:0xf bank_mask:0xf
	v_mov_b32_dpp v23, v37 row_shr:1 row_mask:0xf bank_mask:0xf
	v_mov_b32_dpp v24, v37 row_shr:2 row_mask:0xf bank_mask:0xf
	v_fmac_f32_e32 v78, v34, v74
	v_fmac_f32_e32 v57, v65, v24
	v_fmac_f32_e32 v57, v69, v23
	v_fmac_f32_e32 v55, v35, v75
	v_fmac_f32_e32 v54, v36, v76
	v_fmac_f32_e32 v57, v37, v77
	global_load_dwordx4 v[26:29], v[30:31], off offset:3088
	global_load_dwordx4 v[22:25], v[46:47], off offset:3088
	v_add_co_u32_e32 v30, vcc, 0x2000, v200
	v_mov_b32_e32 v46, 0
	s_nop 0
	v_addc_co_u32_e32 v31, vcc, 0, v201, vcc
	global_load_dwordx4 v[34:37], v[30:31], off offset:3088
	v_add_co_u32_e32 v30, vcc, 0x2000, v198
	v_mov_b32_e32 v47, 0
	s_nop 0
	v_addc_co_u32_e32 v31, vcc, 0, v199, vcc
	global_load_dwordx4 v[38:41], v[30:31], off offset:3088
	s_and_b64 vcc, exec, s[10:11]
	v_mov_b32_e32 v62, 0
	v_mov_b32_e32 v63, 0
	v_mov_b32_e32 v64, 0
	v_mov_b32_e32 v65, 0
	s_cbranch_vccnz .LBB0_1198
	v_add_u32_e32 v31, 0xfffffa10, v227
	v_add_u32_e32 v30, 0xfffffe10, v227
	ds_read_b128 v[44:47], v31
	ds_read_b128 v[62:65], v30
; #define PG8_LAS __attribute__((address_space(3)))
;     __device__ __forceinline__ void operator()(f32x4 (&acc)[2][2][4][2], const Unit& u, int ui, int wr, int wc, int fr_, int fq_) const {
;     ...
;             for (int m = 0; m < 4; ++m) { const float r = rtab[ui * 256 + ai * HALF + wr * 64 + m * 16 + fr];
; #pragma unroll
;                 for (int bj = 0; bj < 2; ++bj)
; #pragma unroll
;                     for (int n = 0; n < 2; ++n) acc[ai][bj][m][n] = acc[ai][bj][m][n] * r; }
;     ...
;             for (int n = 0; n < 2; ++n) { const int ch = bj * 2816 + fbase + 4 * n;
;                 const f32x4 w0 = *(const f32x4*)(cw + ch), w1 = *(const f32x4*)(cw + 5632 + ch), w2 = *(const f32x4*)(cw + 2 * 5632 + ch), bb = *(const f32x4*)(cb + ch);
; #pragma unroll
;                 for (int ai = 0; ai < 2; ++ai) { const int kb = 2 * ai + wr;
;                     f32x4 c62 = (f32x4){0.f, 0.f, 0.f, 0.f}, c63 = c62;
;                     if (kb > 0) { c62 = *(const PG8_LAS f32x4*)(exch + (((kb - 1) * 2 + 0) * 256 + bj * HALF + 32 * wc + 8 * fq + 4 * n)); c63 = *(const PG8_LAS f32x4*)(exch + (((kb - 1) * 2 + 1) * 256 + bj * HALF + 32 * wc + 8 * fq + 4 * n)); }
; #pragma unroll
;                     for (int m = 3; m >= 0; --m) { f32x4 cur = acc[ai][bj][m][n], res;
; #pragma unroll
;                         for (int j = 0; j < 4; ++j) { const float c = cur[j]; const float pv = (m > 0) ? acc[ai][bj][m > 0 ? m - 1 : 0][n][j] : (fr == 15 ? c63[j] : c62[j]); float t1, t2;
;                             asm volatile("s_nop 1\n\tv_mov_b32_dpp %0, %3 row_ror:1 row_mask:0xf bank_mask:0xf\n\tv_mov_b32_dpp %1, %3 row_ror:2 row_mask:0xf bank_mask:0xf\n\t"
;                                          "v_mov_b32_dpp %0, %2 row_shr:1 row_mask:0xf bank_mask:0xf\n\tv_mov_b32_dpp %1, %2 row_shr:2 row_mask:0xf bank_mask:0xf"
;                                          : "=&v"(t1), "=&v"(t2) : "v"(c), "v"(pv));
;                             res[j] = bb[j] + w0[j] * t2 + w1[j] * t1 + w2[j] * c; }
;                         asm volatile("" : "+v"(res[0]), "+v"(res[1]), "+v"(res[2]), "+v"(res[3]));
;                         acc[ai][bj][m][n] = res; } }
.LBB0_1198:
	v_mov_b32_e32 v30, v194
	v_mov_b32_e32 v31, v194
	v_pk_mul_f32 v[76:77], v[18:19], v[194:195]
	v_mov_b32_e32 v18, v196
	v_mov_b32_e32 v19, v196
	v_pk_mul_f32 v[74:75], v[20:21], v[30:31]
	v_pk_mul_f32 v[16:17], v[16:17], v[18:19]
	v_pk_mul_f32 v[14:15], v[14:15], v[196:197]
	s_and_b64 vcc, exec, s[12:13]
	s_waitcnt vmcnt(0)
	v_mov_b32_e32 v20, v38
	v_fmac_f32_dpp v20, v70, v26 row_shr:2 row_mask:0xf bank_mask:0xf
	v_fmac_f32_dpp v20, v14, v26 row_shl:14 row_mask:0xf bank_mask:0xf
	v_fmac_f32_dpp v20, v70, v22 row_shr:1 row_mask:0xf bank_mask:0xf
	v_fmac_f32_dpp v20, v14, v22 row_shl:15 row_mask:0xf bank_mask:0xf
	v_fmac_f32_e32 v20, v70, v34
	v_mov_b32_e32 v18, v39
	v_fmac_f32_dpp v18, v71, v27 row_shr:2 row_mask:0xf bank_mask:0xf
	v_fmac_f32_dpp v18, v15, v27 row_shl:14 row_mask:0xf bank_mask:0xf
	v_fmac_f32_dpp v18, v71, v23 row_shr:1 row_mask:0xf bank_mask:0xf
	v_fmac_f32_dpp v18, v15, v23 row_shl:15 row_mask:0xf bank_mask:0xf
	v_fmac_f32_e32 v18, v71, v35
	v_mov_b32_e32 v19, v40
	v_fmac_f32_dpp v19, v72, v28 row_shr:2 row_mask:0xf bank_mask:0xf
	v_fmac_f32_dpp v19, v16, v28 row_shl:14 row_mask:0xf bank_mask:0xf
	v_fmac_f32_dpp v19, v72, v24 row_shr:1 row_mask:0xf bank_mask:0xf
	v_fmac_f32_dpp v19, v16, v24 row_shl:15 row_mask:0xf bank_mask:0xf
	v_fmac_f32_e32 v19, v72, v36
	v_mov_b32_e32 v21, v41
	v_fmac_f32_dpp v21, v73, v29 row_shr:2 row_mask:0xf bank_mask:0xf
	v_fmac_f32_dpp v21, v17, v29 row_shl:14 row_mask:0xf bank_mask:0xf
	v_fmac_f32_dpp v21, v73, v25 row_shr:1 row_mask:0xf bank_mask:0xf
	v_fmac_f32_dpp v21, v17, v25 row_shl:15 row_mask:0xf bank_mask:0xf
	v_fmac_f32_e32 v21, v73, v37
	s_nop 0
	v_mov_b32_e32 v56, v38
	v_fmac_f32_dpp v56, v14, v26 row_shr:2 row_mask:0xf bank_mask:0xf
	v_fmac_f32_dpp v56, v76, v26 row_shl:14 row_mask:0xf bank_mask:0xf
	v_fmac_f32_dpp v56, v14, v22 row_shr:1 row_mask:0xf bank_mask:0xf
	v_fmac_f32_dpp v56, v76, v22 row_shl:15 row_mask:0xf bank_mask:0xf
	v_fmac_f32_e32 v56, v14, v34
	s_nop 0
	v_mov_b32_e32 v30, v39
	v_fmac_f32_dpp v30, v15, v27 row_shr:2 row_mask:0xf bank_mask:0xf
	v_fmac_f32_dpp v30, v77, v27 row_shl:14 row_mask:0xf bank_mask:0xf
	v_fmac_f32_dpp v30, v15, v23 row_shr:1 row_mask:0xf bank_mask:0xf
	v_fmac_f32_dpp v30, v77, v23 row_shl:15 row_mask:0xf bank_mask:0xf
	v_fmac_f32_e32 v30, v15, v35
	s_nop 0
	v_mov_b32_e32 v31, v40
	v_fmac_f32_dpp v31, v16, v28 row_shr:2 row_mask:0xf bank_mask:0xf
	v_fmac_f32_dpp v31, v74, v28 row_shl:14 row_mask:0xf bank_mask:0xf
	v_fmac_f32_dpp v31, v16, v24 row_shr:1 row_mask:0xf bank_mask:0xf
	v_fmac_f32_dpp v31, v74, v24 row_shl:15 row_mask:0xf bank_mask:0xf
	v_fmac_f32_e32 v31, v16, v36
	v_mov_b32_e32 v66, v41
	v_fmac_f32_dpp v66, v17, v29 row_shr:2 row_mask:0xf bank_mask:0xf
	v_fmac_f32_dpp v66, v75, v29 row_shl:14 row_mask:0xf bank_mask:0xf
	v_fmac_f32_dpp v66, v17, v25 row_shr:1 row_mask:0xf bank_mask:0xf
	v_fmac_f32_dpp v66, v75, v25 row_shl:15 row_mask:0xf bank_mask:0xf
	v_fmac_f32_e32 v66, v17, v37
	s_waitcnt lgkmcnt(0)
	v_cndmask_b32_e64 v17, v44, v62, s[8:9]
	v_mov_b32_e32 v69, v38
	v_fmac_f32_dpp v69, v76, v26 row_shr:2 row_mask:0xf bank_mask:0xf
	v_fmac_f32_dpp v69, v58, v26 row_shl:14 row_mask:0xf bank_mask:0xf
	v_fmac_f32_dpp v69, v76, v22 row_shr:1 row_mask:0xf bank_mask:0xf
	v_fmac_f32_dpp v69, v58, v22 row_shl:15 row_mask:0xf bank_mask:0xf
	v_fmac_f32_e32 v69, v76, v34
	v_mov_b32_e32 v67, v39
	v_fmac_f32_dpp v67, v77, v27 row_shr:2 row_mask:0xf bank_mask:0xf
	v_fmac_f32_dpp v67, v59, v27 row_shl:14 row_mask:0xf bank_mask:0xf
	v_fmac_f32_dpp v67, v77, v23 row_shr:1 row_mask:0xf bank_mask:0xf
	v_fmac_f32_dpp v67, v59, v23 row_shl:15 row_mask:0xf bank_mask:0xf
	v_fmac_f32_e32 v67, v77, v35
	v_mov_b32_e32 v68, v40
	v_fmac_f32_dpp v68, v74, v28 row_shr:2 row_mask:0xf bank_mask:0xf
	v_fmac_f32_dpp v68, v60, v28 row_shl:14 row_mask:0xf bank_mask:0xf
	v_fmac_f32_dpp v68, v74, v24 row_shr:1 row_mask:0xf bank_mask:0xf
	v_fmac_f32_dpp v68, v60, v24 row_shl:15 row_mask:0xf bank_mask:0xf
	v_fmac_f32_e32 v68, v74, v36
	v_mov_b32_e32 v70, v41
	v_fmac_f32_dpp v70, v75, v29 row_shr:2 row_mask:0xf bank_mask:0xf
	v_fmac_f32_dpp v70, v61, v29 row_shl:14 row_mask:0xf bank_mask:0xf
	v_fmac_f32_dpp v70, v75, v25 row_shr:1 row_mask:0xf bank_mask:0xf
	v_fmac_f32_dpp v70, v61, v25 row_shl:15 row_mask:0xf bank_mask:0xf
	v_fmac_f32_e32 v70, v75, v37
	v_cndmask_b32_e64 v16, v45, v63, s[8:9]
	v_mov_b32_e32 v62, v38
	v_fmac_f32_dpp v62, v58, v26 row_shr:2 row_mask:0xf bank_mask:0xf
	v_fmac_f32_dpp v62, v17, v26 row_shl:14 row_mask:0xf bank_mask:0xf
	v_fmac_f32_dpp v62, v58, v22 row_shr:1 row_mask:0xf bank_mask:0xf
	v_fmac_f32_dpp v62, v17, v22 row_shl:15 row_mask:0xf bank_mask:0xf
	v_fmac_f32_e32 v62, v58, v34
	v_cndmask_b32_e64 v15, v46, v64, s[8:9]
	v_mov_b32_e32 v58, v39
	v_fmac_f32_dpp v58, v59, v27 row_shr:2 row_mask:0xf bank_mask:0xf
	v_fmac_f32_dpp v58, v16, v27 row_shl:14 row_mask:0xf bank_mask:0xf
	v_fmac_f32_dpp v58, v59, v23 row_shr:1 row_mask:0xf bank_mask:0xf
	v_fmac_f32_dpp v58, v16, v23 row_shl:15 row_mask:0xf bank_mask:0xf
	v_fmac_f32_e32 v58, v59, v35
	v_cndmask_b32_e64 v14, v47, v65, s[8:9]
	v_mov_b32_e32 v59, v40
	v_fmac_f32_dpp v59, v60, v28 row_shr:2 row_mask:0xf bank_mask:0xf
	v_fmac_f32_dpp v59, v15, v28 row_shl:14 row_mask:0xf bank_mask:0xf
	v_fmac_f32_dpp v59, v60, v24 row_shr:1 row_mask:0xf bank_mask:0xf
	v_fmac_f32_dpp v59, v15, v24 row_shl:15 row_mask:0xf bank_mask:0xf
	v_fmac_f32_e32 v59, v60, v36
	v_mov_b32_e32 v43, 0
	v_mov_b32_e32 v60, v41
	v_fmac_f32_dpp v60, v61, v29 row_shr:2 row_mask:0xf bank_mask:0xf
	v_fmac_f32_dpp v60, v14, v29 row_shl:14 row_mask:0xf bank_mask:0xf
	v_fmac_f32_dpp v60, v61, v25 row_shr:1 row_mask:0xf bank_mask:0xf
	v_fmac_f32_dpp v60, v14, v25 row_shl:15 row_mask:0xf bank_mask:0xf
	v_fmac_f32_e32 v60, v61, v37
	v_mov_b32_e32 v44, 0
	v_mov_b32_e32 v45, 0
	v_mov_b32_e32 v14, 0
	v_mov_b32_e32 v15, 0
	v_mov_b32_e32 v16, 0
	v_mov_b32_e32 v17, 0
	s_cbranch_vccnz .LBB0_1200
	ds_read_b128 v[42:45], v227 offset:2576
	ds_read_b128 v[14:17], v227 offset:3600
